# hot-loop heads 64-byte aligned (.p2align 6 on the 8 GEMM k-loop labels and the RWKV/HGRN token-loop labels)
# baseline (speedup 1.0000x reference)
.Lg1a_cont:
	s_lshl3_add_u32 s22, s5, s25
	s_lshl_b32 s23, s6, 1
	s_mul_i32 s0, s22, 0x40000
	s_add_u32 s14, s44, s0
	s_addc_u32 s15, s45, 0
	s_mul_i32 s0, s23, 0x40000
	s_add_u32 s16, s48, s0
	s_addc_u32 s17, s49, 0
	s_add_u32 s18, s16, 0x40000
	s_addc_u32 s19, s17, 0
	s_lshl_b32 s0, s22, 9
	s_add_u32 s30, s90, s0
	s_addc_u32 s31, s91, 0
	s_waitcnt vmcnt(0) lgkmcnt(0)
	s_barrier
	v_and_b32_e32 v166, 63, v148
	v_lshlrev_b32_e32 v166, 4, v166
	s_mov_b32 m0, 0xc400
	s_mov_b64 exec, 0xffffffff
	global_load_lds_dwordx4 v166, s[30:31]
	s_mov_b64 exec, -1
	s_add_u32 m0, s20, 0x0
	s_nop 0
	global_load_lds_dwordx4 v160, s[14:15]
	global_load_lds_dwordx4 v160, s[14:15] offset:1024
	s_add_u32 s14, s14, 0x2000
	s_addc_u32 s15, s15, 0
	s_add_u32 m0, s20, 0x2000
	s_nop 0
	global_load_lds_dwordx4 v160, s[16:17]
	global_load_lds_dwordx4 v160, s[16:17] offset:1024
	s_add_u32 s16, s16, 0x2000
	s_addc_u32 s17, s17, 0
	s_add_u32 m0, s20, 0x4000
	s_nop 0
	global_load_lds_dwordx4 v160, s[18:19]
	global_load_lds_dwordx4 v160, s[18:19] offset:1024
	s_add_u32 s18, s18, 0x2000
	s_addc_u32 s19, s19, 0
	s_waitcnt vmcnt(0)
	s_barrier
	s_add_u32 m0, s20, 0x6000
	s_nop 0
	global_load_lds_dwordx4 v160, s[14:15]
	global_load_lds_dwordx4 v160, s[14:15] offset:1024
	s_add_u32 s14, s14, 0x2000
	s_addc_u32 s15, s15, 0
	s_add_u32 m0, s20, 0x8000
	s_nop 0
	global_load_lds_dwordx4 v160, s[16:17]
	global_load_lds_dwordx4 v160, s[16:17] offset:1024
	s_add_u32 s16, s16, 0x2000
	s_addc_u32 s17, s17, 0
	s_add_u32 m0, s20, 0xa400
	s_nop 0
	global_load_lds_dwordx4 v160, s[18:19]
	global_load_lds_dwordx4 v160, s[18:19] offset:1024
	s_add_u32 s18, s18, 0x2000
	s_addc_u32 s19, s19, 0
	ds_read_b128 v[64:67], v154 offset:0
	ds_read_b128 v[72:75], v156 offset:8192
	ds_read_b128 v[76:79], v156 offset:10240
	ds_read_b128 v[80:83], v156 offset:16384
	ds_read_b128 v[150:153], v156 offset:18432
	ds_read_b128 v[68:71], v154 offset:2048
	s_waitcnt lgkmcnt(4)
	v_mfma_f32_32x32x16_bf16 v[48:63], v[64:67], v[72:75], 0
	s_waitcnt lgkmcnt(3)
	v_mfma_f32_32x32x16_bf16 v[32:47], v[64:67], v[76:79], 0
	s_waitcnt lgkmcnt(2)
	v_mfma_f32_32x32x16_bf16 v[132:147], v[64:67], v[80:83], 0
	s_waitcnt lgkmcnt(1)
	v_mfma_f32_32x32x16_bf16 v[116:131], v[64:67], v[150:153], 0
	ds_read_b128 v[64:67], v155 offset:0
	s_waitcnt lgkmcnt(1)
	v_mfma_f32_32x32x16_bf16 v[84:99], v[68:71], v[150:153], 0
	ds_read_b128 v[150:153], v157 offset:18432
	v_mfma_f32_32x32x16_bf16 v[100:115], v[68:71], v[80:83], 0
	ds_read_b128 v[80:83], v157 offset:16384
	v_mfma_f32_32x32x16_bf16 v[0:15], v[68:71], v[76:79], 0
	ds_read_b128 v[76:79], v157 offset:10240
	v_mfma_f32_32x32x16_bf16 v[16:31], v[68:71], v[72:75], 0
	ds_read_b128 v[72:75], v157 offset:8192
	ds_read_b128 v[68:71], v155 offset:2048
	s_waitcnt lgkmcnt(4)
	v_mfma_f32_32x32x16_bf16 v[116:131], v[64:67], v[150:153], v[116:131]
	s_waitcnt lgkmcnt(3)
	v_mfma_f32_32x32x16_bf16 v[132:147], v[64:67], v[80:83], v[132:147]
	s_waitcnt lgkmcnt(2)
	v_mfma_f32_32x32x16_bf16 v[32:47], v[64:67], v[76:79], v[32:47]
	s_waitcnt lgkmcnt(1)
	v_mfma_f32_32x32x16_bf16 v[48:63], v[64:67], v[72:75], v[48:63]
	s_waitcnt vmcnt(0) lgkmcnt(0)
	s_barrier
	ds_read_b128 v[64:67], v154 offset:24576
	s_add_u32 m0, s20, 0x0
	s_nop 0
	global_load_lds_dwordx4 v160, s[14:15]
	global_load_lds_dwordx4 v160, s[14:15] offset:1024
	s_add_u32 s14, s14, 0x2000
	s_addc_u32 s15, s15, 0
	v_mfma_f32_32x32x16_bf16 v[16:31], v[68:71], v[72:75], v[16:31]
	ds_read_b128 v[72:75], v156 offset:32768
	s_add_u32 m0, s20, 0x2000
	s_nop 0
	global_load_lds_dwordx4 v160, s[16:17]
	global_load_lds_dwordx4 v160, s[16:17] offset:1024
	s_add_u32 s16, s16, 0x2000
	s_addc_u32 s17, s17, 0
	v_mfma_f32_32x32x16_bf16 v[0:15], v[68:71], v[76:79], v[0:15]
	ds_read_b128 v[76:79], v156 offset:34816
	s_add_u32 m0, s20, 0x4000
	s_nop 0
	global_load_lds_dwordx4 v160, s[18:19]
	global_load_lds_dwordx4 v160, s[18:19] offset:1024
	s_add_u32 s18, s18, 0x2000
	s_addc_u32 s19, s19, 0
	v_mfma_f32_32x32x16_bf16 v[100:115], v[68:71], v[80:83], v[100:115]
	ds_read_b128 v[80:83], v156 offset:41984
	v_mfma_f32_32x32x16_bf16 v[84:99], v[68:71], v[150:153], v[84:99]
	ds_read_b128 v[150:153], v156 offset:44032
	ds_read_b128 v[68:71], v154 offset:26624
	s_waitcnt lgkmcnt(4)
	v_mfma_f32_32x32x16_bf16 v[48:63], v[64:67], v[72:75], v[48:63]
	s_waitcnt lgkmcnt(3)
	v_mfma_f32_32x32x16_bf16 v[32:47], v[64:67], v[76:79], v[32:47]
	s_waitcnt lgkmcnt(2)
	v_mfma_f32_32x32x16_bf16 v[132:147], v[64:67], v[80:83], v[132:147]
	s_waitcnt lgkmcnt(1)
	v_mfma_f32_32x32x16_bf16 v[116:131], v[64:67], v[150:153], v[116:131]
	ds_read_b128 v[64:67], v155 offset:24576
	s_waitcnt lgkmcnt(1)
	v_mfma_f32_32x32x16_bf16 v[84:99], v[68:71], v[150:153], v[84:99]
	ds_read_b128 v[150:153], v157 offset:44032
	v_mfma_f32_32x32x16_bf16 v[100:115], v[68:71], v[80:83], v[100:115]
	ds_read_b128 v[80:83], v157 offset:41984
	v_mfma_f32_32x32x16_bf16 v[0:15], v[68:71], v[76:79], v[0:15]
	ds_read_b128 v[76:79], v157 offset:34816
	v_mfma_f32_32x32x16_bf16 v[16:31], v[68:71], v[72:75], v[16:31]
	ds_read_b128 v[72:75], v157 offset:32768
	ds_read_b128 v[68:71], v155 offset:26624
	s_waitcnt lgkmcnt(4)
	v_mfma_f32_32x32x16_bf16 v[116:131], v[64:67], v[150:153], v[116:131]
	s_waitcnt lgkmcnt(3)
	v_mfma_f32_32x32x16_bf16 v[132:147], v[64:67], v[80:83], v[132:147]
	s_waitcnt lgkmcnt(2)
	v_mfma_f32_32x32x16_bf16 v[32:47], v[64:67], v[76:79], v[32:47]
	s_waitcnt lgkmcnt(1)
	v_mfma_f32_32x32x16_bf16 v[48:63], v[64:67], v[72:75], v[48:63]
	s_waitcnt vmcnt(0) lgkmcnt(0)
	s_barrier
	ds_read_b128 v[64:67], v154 offset:0
	s_add_u32 m0, s20, 0x6000
	s_nop 0
	global_load_lds_dwordx4 v160, s[14:15]
	global_load_lds_dwordx4 v160, s[14:15] offset:1024
	s_add_u32 s14, s14, 0x2000
	s_addc_u32 s15, s15, 0
	v_mfma_f32_32x32x16_bf16 v[16:31], v[68:71], v[72:75], v[16:31]
	ds_read_b128 v[72:75], v156 offset:8192
	s_add_u32 m0, s20, 0x8000
	s_nop 0
	global_load_lds_dwordx4 v160, s[16:17]
	global_load_lds_dwordx4 v160, s[16:17] offset:1024
	s_add_u32 s16, s16, 0x2000
	s_addc_u32 s17, s17, 0
	v_mfma_f32_32x32x16_bf16 v[0:15], v[68:71], v[76:79], v[0:15]
	ds_read_b128 v[76:79], v156 offset:10240
	s_add_u32 m0, s20, 0xa400
	s_nop 0
	global_load_lds_dwordx4 v160, s[18:19]
	global_load_lds_dwordx4 v160, s[18:19] offset:1024
	s_add_u32 s18, s18, 0x2000
	s_addc_u32 s19, s19, 0
	v_mfma_f32_32x32x16_bf16 v[100:115], v[68:71], v[80:83], v[100:115]
	ds_read_b128 v[80:83], v156 offset:16384
	v_mfma_f32_32x32x16_bf16 v[84:99], v[68:71], v[150:153], v[84:99]
	ds_read_b128 v[150:153], v156 offset:18432
	ds_read_b128 v[68:71], v154 offset:2048
	s_mov_b32 s21, 14
	.p2align 6

.LBB0_345:
	v_add_u32_e32 v1, s4, v21
	v_mov_b64_e32 v[4:5], s[46:47]
	v_mad_i64_i32 v[32:33], s[0:1], v1, s56, v[4:5]
	s_lshl_b32 s12, s29, 1
	v_lshlrev_b32_e32 v2, 1, v38
	v_lshl_add_u64 v[4:5], v[32:33], 0, s[12:13]
	v_lshl_add_u64 v[4:5], v[4:5], 0, v[2:3]
	s_add_i32 s0, s29, s27
	v_add_co_u32_e32 v6, vcc, 0x1000, v4
	s_addk_i32 s0, 0x1300
	s_nop 0
	v_addc_co_u32_e32 v7, vcc, 0, v5, vcc
	v_or_b32_e32 v40, s0, v20
	v_add_co_u32_e32 v8, vcc, s55, v4
	v_lshlrev_b32_e32 v2, 1, v40
	s_nop 0
	v_addc_co_u32_e32 v9, vcc, 0, v5, vcc
	v_lshl_add_u64 v[32:33], v[32:33], 0, v[2:3]
	global_load_dwordx4 v[4:7], v[6:7], off offset:3584
	s_nop 0
	global_load_dwordx4 v[8:11], v[8:9], off offset:512
	v_lshlrev_b32_e32 v13, 4, v30
	global_load_ushort v39, v[32:33], off
	v_and_b32_e32 v2, 63, v30
	v_and_b32_e32 v13, 48, v13
	v_add_u32_e32 v13, v31, v13
	v_or_b32_e32 v2, 0x200, v2
	v_cmp_gt_u32_e32 vcc, 4, v20
	v_lshlrev_b32_e32 v44, 2, v31
	s_mov_b32 s30, 1
	v_cndmask_b32_e32 v2, v2, v13, vcc
	v_lshlrev_b32_e32 v13, 2, v38
	v_lshl_or_b32 v15, v21, 9, v13
	v_and_b32_e32 v13, 1, v30
	v_cmp_eq_u32_e64 s[0:1], 0, v13
	v_and_b32_e32 v13, 2, v30
	v_cmp_eq_u32_e64 s[4:5], 0, v13
	v_and_b32_e32 v13, -16, v30
	v_cndmask_b32_e64 v41, 0, 16, vcc
	v_lshlrev_b32_e32 v45, 2, v2
	v_or_b32_e32 v2, v13, v20
	s_mov_b32 s31, 0
	v_lshlrev_b32_e32 v17, 2, v30
	v_lshlrev_b32_e32 v21, 4, v20
	v_lshlrev_b32_e32 v46, 2, v2
	v_pk_add_f32 v[30:31], v[22:23], 1.0 op_sel_hi:[1,0] neg_lo:[1,0] neg_hi:[1,0]
	v_pk_add_f32 v[32:33], v[24:25], 1.0 op_sel_hi:[1,0] neg_lo:[1,0] neg_hi:[1,0]
	v_pk_add_f32 v[34:35], v[26:27], 1.0 op_sel_hi:[1,0] neg_lo:[1,0] neg_hi:[1,0]
	v_pk_add_f32 v[36:37], v[28:29], 1.0 op_sel_hi:[1,0] neg_lo:[1,0] neg_hi:[1,0]
	v_lshlrev_b32_e32 v47, 4, v41
	v_lshlrev_b32_e32 v48, 5, v41
	v_mul_u32_u24_e32 v49, 48, v41
	s_lshl_b32 s59, s28, 8
	v_lshlrev_b32_e32 v38, 1, v38
	v_lshlrev_b32_e32 v40, 1, v40
	v_lshlrev_b32_e32 v2, 1, v20
	v_add_u32_e32 v50, 0x6000, v44
	v_mov_b32_e32 v51, v1
	s_movk_i32 s77, 0x7400
	s_movk_i32 s78, 0x5400
	s_barrier
	s_branch .LBB0_347
	.p2align 6

.LBB0_389:
	v_add_u32_e32 v1, s8, v24
	v_mov_b64_e32 v[12:13], s[46:47]
	v_mad_i64_i32 v[26:27], s[2:3], v1, s56, v[12:13]
	v_mov_b64_e32 v[12:13], s[88:89]
	v_mad_i64_i32 v[14:15], s[2:3], v1, s58, v[12:13]
	s_lshl_b32 s2, s5, 6
	s_lshl_b32 s12, s5, 7
	v_lshl_add_u64 v[16:17], v[26:27], 0, s[12:13]
	v_lshlrev_b32_e32 v12, 1, v0
	v_mov_b32_e32 v13, v3
	s_or_b32 s3, s7, s2
	v_lshl_add_u64 v[16:17], v[16:17], 0, v[12:13]
	v_or_b32_e32 v2, s3, v10
	v_add_co_u32_e32 v18, vcc, s57, v16
	v_lshl_add_u64 v[14:15], v[14:15], 0, s[12:13]
	v_or_b32_e32 v28, 0xc00, v2
	v_addc_co_u32_e32 v19, vcc, 0, v17, vcc
	v_lshl_add_u64 v[22:23], v[14:15], 0, v[12:13]
	v_lshlrev_b32_e32 v2, 1, v28
	global_load_dwordx2 v[16:17], v[16:17], off offset:1024
	s_nop 0
	global_load_dwordx2 v[20:21], v[18:19], off offset:1024
	global_load_dwordx2 v[14:15], v[22:23], off
	s_nop 0
	global_load_dwordx2 v[18:19], v[22:23], off offset:1024
	s_nop 0
	global_load_dwordx2 v[22:23], v[22:23], off offset:2048
	v_lshl_add_u64 v[26:27], v[26:27], 0, v[2:3]
	global_load_ushort v27, v[26:27], off
	v_and_b32_e32 v2, 63, v11
	v_or_b32_e32 v2, 0x200, v2
	v_cmp_eq_u32_e32 vcc, 0, v10
	v_lshlrev_b32_e32 v30, 2, v0
	v_lshlrev_b32_e32 v32, 2, v11
	v_and_b32_e32 v11, -16, v11
	s_add_u32 s24, s88, s12
	v_cndmask_b32_e32 v2, v2, v25, vcc
	v_cndmask_b32_e64 v26, 0, 16, vcc
	v_lshl_or_b32 v31, v24, 8, v30
	v_or_b32_e32 v24, v11, v10
	s_addc_u32 s25, s89, 0
	s_mov_b32 s3, 1
	s_mov_b32 s8, 0
	v_lshlrev_b32_e32 v33, 2, v25
	v_mul_u32_u24_e32 v34, 60, v26
	v_lshlrev_b32_e32 v35, 2, v24
	v_lshlrev_b32_e32 v36, 2, v2
	v_lshlrev_b32_e32 v37, 3, v26
	v_mul_u32_u24_e32 v38, 12, v26
	v_lshlrev_b32_e32 v39, 4, v26
	v_mul_u32_u24_e32 v40, 20, v26
	v_mul_u32_u24_e32 v41, 24, v26
	v_mul_u32_u24_e32 v44, 28, v26
	v_lshlrev_b32_e32 v45, 5, v26
	v_mul_u32_u24_e32 v46, 36, v26
	v_mul_u32_u24_e32 v47, 40, v26
	v_mul_u32_u24_e32 v48, 44, v26
	v_mul_u32_u24_e32 v49, 48, v26
	v_mul_u32_u24_e32 v50, 52, v26
	v_mul_u32_u24_e32 v51, 56, v26
	v_lshl_add_u64 v[24:25], s[24:25], 0, v[12:13]
	v_mul_i32_i24_e32 v52, 0xffffffc8, v26
	s_lshl_b32 s9, s6, 8
	v_lshlrev_b32_e32 v26, 1, v28
	v_mov_b32_e32 v28, v1
	s_movk_i32 s76, 0x6400
	s_barrier
	s_branch .LBB0_391
	.p2align 6

.Lg2a_cont:
	s_lshl3_add_u32 s30, s7, s33
	s_lshl_b32 s31, s11, 1
	s_mul_i32 s2, s30, 0x150000
	s_add_u32 s22, s46, s2
	s_addc_u32 s23, s47, 0
	s_mul_i32 s2, s31, 0x60000
	s_add_u32 s2, s2, 0xa80000
	s_add_u32 s24, s48, s2
	s_addc_u32 s25, s49, 0
	s_add_u32 s26, s24, 0x60000
	s_addc_u32 s27, s25, 0
	s_waitcnt vmcnt(0) lgkmcnt(0)
	s_barrier
	s_add_u32 m0, s28, 0x0
	s_nop 0
	global_load_lds_dwordx4 v166, s[22:23]
	s_add_u32 m0, s28, 0x400
	s_nop 0
	global_load_lds_dwordx4 v167, s[22:23]
	s_add_u32 s22, s22, 64
	s_addc_u32 s23, s23, 0
	s_add_u32 m0, s28, 0x2000
	s_nop 0
	global_load_lds_dwordx4 v165, s[24:25]
	global_load_lds_dwordx4 v165, s[24:25] offset:1024
	s_add_u32 s24, s24, 0x2000
	s_addc_u32 s25, s25, 0
	s_add_u32 m0, s28, 0x4000
	s_nop 0
	global_load_lds_dwordx4 v165, s[26:27]
	global_load_lds_dwordx4 v165, s[26:27] offset:1024
	s_add_u32 s26, s26, 0x2000
	s_addc_u32 s27, s27, 0
	s_waitcnt vmcnt(0)
	s_barrier
	s_add_u32 m0, s28, 0x6000
	s_nop 0
	global_load_lds_dwordx4 v166, s[22:23]
	s_add_u32 m0, s28, 0x6400
	s_nop 0
	global_load_lds_dwordx4 v167, s[22:23]
	s_add_u32 s22, s22, 64
	s_addc_u32 s23, s23, 0
	s_add_u32 m0, s28, 0x8000
	s_nop 0
	global_load_lds_dwordx4 v165, s[24:25]
	global_load_lds_dwordx4 v165, s[24:25] offset:1024
	s_add_u32 s24, s24, 0x2000
	s_addc_u32 s25, s25, 0
	s_add_u32 m0, s28, 0xa400
	s_nop 0
	global_load_lds_dwordx4 v165, s[26:27]
	global_load_lds_dwordx4 v165, s[26:27] offset:1024
	s_add_u32 s26, s26, 0x2000
	s_addc_u32 s27, s27, 0
	ds_read_b128 v[64:67], v151 offset:0
	ds_read_b128 v[72:75], v157 offset:8192
	ds_read_b128 v[126:129], v157 offset:10240
	ds_read_b128 v[152:155], v157 offset:16384
	ds_read_b128 v[160:163], v157 offset:18432
	ds_read_b128 v[68:71], v151 offset:2048
	s_waitcnt lgkmcnt(4)
	v_mfma_f32_32x32x16_bf16 v[48:63], v[64:67], v[72:75], 0
	s_waitcnt lgkmcnt(3)
	v_mfma_f32_32x32x16_bf16 v[32:47], v[64:67], v[126:129], 0
	s_waitcnt lgkmcnt(2)
	v_mfma_f32_32x32x16_bf16 v[78:93], v[64:67], v[152:155], 0
	s_waitcnt lgkmcnt(1)
	v_mfma_f32_32x32x16_bf16 v[94:109], v[64:67], v[160:163], 0
	ds_read_b128 v[64:67], v156 offset:0
	s_waitcnt lgkmcnt(1)
	v_mfma_f32_32x32x16_bf16 v[132:147], v[68:71], v[160:163], 0
	ds_read_b128 v[160:163], v164 offset:18432
	v_mfma_f32_32x32x16_bf16 v[110:125], v[68:71], v[152:155], 0
	ds_read_b128 v[152:155], v164 offset:16384
	v_mfma_f32_32x32x16_bf16 v[0:15], v[68:71], v[126:129], 0
	ds_read_b128 v[126:129], v164 offset:10240
	v_mfma_f32_32x32x16_bf16 v[16:31], v[68:71], v[72:75], 0
	ds_read_b128 v[72:75], v164 offset:8192
	ds_read_b128 v[68:71], v156 offset:2048
	s_waitcnt lgkmcnt(4)
	v_mfma_f32_32x32x16_bf16 v[94:109], v[64:67], v[160:163], v[94:109]
	s_waitcnt lgkmcnt(3)
	v_mfma_f32_32x32x16_bf16 v[78:93], v[64:67], v[152:155], v[78:93]
	s_waitcnt lgkmcnt(2)
	v_mfma_f32_32x32x16_bf16 v[32:47], v[64:67], v[126:129], v[32:47]
	s_waitcnt lgkmcnt(1)
	v_mfma_f32_32x32x16_bf16 v[48:63], v[64:67], v[72:75], v[48:63]
	s_waitcnt vmcnt(0) lgkmcnt(0)
	s_barrier
	ds_read_b128 v[64:67], v151 offset:24576
	s_add_u32 m0, s28, 0x0
	s_nop 0
	global_load_lds_dwordx4 v166, s[22:23]
	s_add_u32 m0, s28, 0x400
	s_nop 0
	global_load_lds_dwordx4 v167, s[22:23]
	s_add_u32 s22, s22, 64
	s_addc_u32 s23, s23, 0
	v_mfma_f32_32x32x16_bf16 v[16:31], v[68:71], v[72:75], v[16:31]
	ds_read_b128 v[72:75], v157 offset:32768
	s_add_u32 m0, s28, 0x2000
	s_nop 0
	global_load_lds_dwordx4 v165, s[24:25]
	global_load_lds_dwordx4 v165, s[24:25] offset:1024
	s_add_u32 s24, s24, 0x2000
	s_addc_u32 s25, s25, 0
	v_mfma_f32_32x32x16_bf16 v[0:15], v[68:71], v[126:129], v[0:15]
	ds_read_b128 v[126:129], v157 offset:34816
	s_add_u32 m0, s28, 0x4000
	s_nop 0
	global_load_lds_dwordx4 v165, s[26:27]
	global_load_lds_dwordx4 v165, s[26:27] offset:1024
	s_add_u32 s26, s26, 0x2000
	s_addc_u32 s27, s27, 0
	v_mfma_f32_32x32x16_bf16 v[110:125], v[68:71], v[152:155], v[110:125]
	ds_read_b128 v[152:155], v157 offset:41984
	v_mfma_f32_32x32x16_bf16 v[132:147], v[68:71], v[160:163], v[132:147]
	ds_read_b128 v[160:163], v157 offset:44032
	ds_read_b128 v[68:71], v151 offset:26624
	s_waitcnt lgkmcnt(4)
	v_mfma_f32_32x32x16_bf16 v[48:63], v[64:67], v[72:75], v[48:63]
	s_waitcnt lgkmcnt(3)
	v_mfma_f32_32x32x16_bf16 v[32:47], v[64:67], v[126:129], v[32:47]
	s_waitcnt lgkmcnt(2)
	v_mfma_f32_32x32x16_bf16 v[78:93], v[64:67], v[152:155], v[78:93]
	s_waitcnt lgkmcnt(1)
	v_mfma_f32_32x32x16_bf16 v[94:109], v[64:67], v[160:163], v[94:109]
	ds_read_b128 v[64:67], v156 offset:24576
	s_waitcnt lgkmcnt(1)
	v_mfma_f32_32x32x16_bf16 v[132:147], v[68:71], v[160:163], v[132:147]
	ds_read_b128 v[160:163], v164 offset:44032
	v_mfma_f32_32x32x16_bf16 v[110:125], v[68:71], v[152:155], v[110:125]
	ds_read_b128 v[152:155], v164 offset:41984
	v_mfma_f32_32x32x16_bf16 v[0:15], v[68:71], v[126:129], v[0:15]
	ds_read_b128 v[126:129], v164 offset:34816
	v_mfma_f32_32x32x16_bf16 v[16:31], v[68:71], v[72:75], v[16:31]
	ds_read_b128 v[72:75], v164 offset:32768
	ds_read_b128 v[68:71], v156 offset:26624
	s_waitcnt lgkmcnt(4)
	v_mfma_f32_32x32x16_bf16 v[94:109], v[64:67], v[160:163], v[94:109]
	s_waitcnt lgkmcnt(3)
	v_mfma_f32_32x32x16_bf16 v[78:93], v[64:67], v[152:155], v[78:93]
	s_waitcnt lgkmcnt(2)
	v_mfma_f32_32x32x16_bf16 v[32:47], v[64:67], v[126:129], v[32:47]
	s_waitcnt lgkmcnt(1)
	v_mfma_f32_32x32x16_bf16 v[48:63], v[64:67], v[72:75], v[48:63]
	s_waitcnt vmcnt(0) lgkmcnt(0)
	s_barrier
	ds_read_b128 v[64:67], v151 offset:0
	s_add_u32 m0, s28, 0x6000
	s_nop 0
	global_load_lds_dwordx4 v166, s[22:23]
	s_add_u32 m0, s28, 0x6400
	s_nop 0
	global_load_lds_dwordx4 v167, s[22:23]
	s_add_u32 s22, s22, 64
	s_addc_u32 s23, s23, 0
	v_mfma_f32_32x32x16_bf16 v[16:31], v[68:71], v[72:75], v[16:31]
	ds_read_b128 v[72:75], v157 offset:8192
	s_add_u32 m0, s28, 0x8000
	s_nop 0
	global_load_lds_dwordx4 v165, s[24:25]
	global_load_lds_dwordx4 v165, s[24:25] offset:1024
	s_add_u32 s24, s24, 0x2000
	s_addc_u32 s25, s25, 0
	v_mfma_f32_32x32x16_bf16 v[0:15], v[68:71], v[126:129], v[0:15]
	ds_read_b128 v[126:129], v157 offset:10240
	s_add_u32 m0, s28, 0xa400
	s_nop 0
	global_load_lds_dwordx4 v165, s[26:27]
	global_load_lds_dwordx4 v165, s[26:27] offset:1024
	s_add_u32 s26, s26, 0x2000
	s_addc_u32 s27, s27, 0
	v_mfma_f32_32x32x16_bf16 v[110:125], v[68:71], v[152:155], v[110:125]
	ds_read_b128 v[152:155], v157 offset:16384
	v_mfma_f32_32x32x16_bf16 v[132:147], v[68:71], v[160:163], v[132:147]
	ds_read_b128 v[160:163], v157 offset:18432
	ds_read_b128 v[68:71], v151 offset:2048
	s_mov_b32 s29, 22
	.p2align 6

.Lg3a_cont:
	s_lshl3_add_u32 s22, s12, s25
	s_lshl_b32 s23, s13, 1
	s_mul_i32 s8, s22, 0x40000
	s_add_u32 s14, s44, s8
	s_addc_u32 s15, s45, 0
	s_mul_i32 s8, s23, 0x40000
	s_add_u32 s8, s8, 0xd80000
	s_add_u32 s16, s48, s8
	s_addc_u32 s17, s49, 0
	s_add_u32 s18, s16, 0x40000
	s_addc_u32 s19, s17, 0
	s_lshl_b32 s8, s22, 9
	s_add_u32 s30, s4, s8
	s_addc_u32 s31, s5, 0
	s_waitcnt vmcnt(0) lgkmcnt(0)
	s_barrier
	v_and_b32_e32 v167, 63, v148
	v_lshlrev_b32_e32 v167, 4, v167
	s_mov_b32 m0, 0xc400
	s_mov_b64 exec, 0xffffffff
	global_load_lds_dwordx4 v167, s[30:31]
	s_mov_b64 exec, -1
	s_add_u32 m0, s20, 0x0
	s_nop 0
	global_load_lds_dwordx4 v164, s[14:15]
	global_load_lds_dwordx4 v164, s[14:15] offset:1024
	s_add_u32 s14, s14, 0x2000
	s_addc_u32 s15, s15, 0
	s_add_u32 m0, s20, 0x2000
	s_nop 0
	global_load_lds_dwordx4 v164, s[16:17]
	global_load_lds_dwordx4 v164, s[16:17] offset:1024
	s_add_u32 s16, s16, 0x2000
	s_addc_u32 s17, s17, 0
	s_add_u32 m0, s20, 0x4000
	s_nop 0
	global_load_lds_dwordx4 v164, s[18:19]
	global_load_lds_dwordx4 v164, s[18:19] offset:1024
	s_add_u32 s18, s18, 0x2000
	s_addc_u32 s19, s19, 0
	s_waitcnt vmcnt(0)
	s_barrier
	s_add_u32 m0, s20, 0x6000
	s_nop 0
	global_load_lds_dwordx4 v164, s[14:15]
	global_load_lds_dwordx4 v164, s[14:15] offset:1024
	s_add_u32 s14, s14, 0x2000
	s_addc_u32 s15, s15, 0
	s_add_u32 m0, s20, 0x8000
	s_nop 0
	global_load_lds_dwordx4 v164, s[16:17]
	global_load_lds_dwordx4 v164, s[16:17] offset:1024
	s_add_u32 s16, s16, 0x2000
	s_addc_u32 s17, s17, 0
	s_add_u32 m0, s20, 0xa400
	s_nop 0
	global_load_lds_dwordx4 v164, s[18:19]
	global_load_lds_dwordx4 v164, s[18:19] offset:1024
	s_add_u32 s18, s18, 0x2000
	s_addc_u32 s19, s19, 0
	ds_read_b128 v[82:85], v160 offset:0
	ds_read_b128 v[138:141], v162 offset:8192
	ds_read_b128 v[142:145], v162 offset:10240
	ds_read_b128 v[150:153], v162 offset:16384
	ds_read_b128 v[154:157], v162 offset:18432
	ds_read_b128 v[134:137], v160 offset:2048
	s_waitcnt lgkmcnt(4)
	v_mfma_f32_32x32x16_bf16 v[32:47], v[82:85], v[138:141], 0
	s_waitcnt lgkmcnt(3)
	v_mfma_f32_32x32x16_bf16 v[48:63], v[82:85], v[142:145], 0
	s_waitcnt lgkmcnt(2)
	v_mfma_f32_32x32x16_bf16 v[86:101], v[82:85], v[150:153], 0
	s_waitcnt lgkmcnt(1)
	v_mfma_f32_32x32x16_bf16 v[102:117], v[82:85], v[154:157], 0
	ds_read_b128 v[82:85], v161 offset:0
	s_waitcnt lgkmcnt(1)
	v_mfma_f32_32x32x16_bf16 v[66:81], v[134:137], v[154:157], 0
	ds_read_b128 v[154:157], v163 offset:18432
	v_mfma_f32_32x32x16_bf16 v[118:133], v[134:137], v[150:153], 0
	ds_read_b128 v[150:153], v163 offset:16384
	v_mfma_f32_32x32x16_bf16 v[16:31], v[134:137], v[142:145], 0
	ds_read_b128 v[142:145], v163 offset:10240
	v_mfma_f32_32x32x16_bf16 v[0:15], v[134:137], v[138:141], 0
	ds_read_b128 v[138:141], v163 offset:8192
	ds_read_b128 v[134:137], v161 offset:2048
	s_waitcnt lgkmcnt(4)
	v_mfma_f32_32x32x16_bf16 v[102:117], v[82:85], v[154:157], v[102:117]
	s_waitcnt lgkmcnt(3)
	v_mfma_f32_32x32x16_bf16 v[86:101], v[82:85], v[150:153], v[86:101]
	s_waitcnt lgkmcnt(2)
	v_mfma_f32_32x32x16_bf16 v[48:63], v[82:85], v[142:145], v[48:63]
	s_waitcnt lgkmcnt(1)
	v_mfma_f32_32x32x16_bf16 v[32:47], v[82:85], v[138:141], v[32:47]
	s_waitcnt vmcnt(0) lgkmcnt(0)
	s_barrier
	ds_read_b128 v[82:85], v160 offset:24576
	s_add_u32 m0, s20, 0x0
	s_nop 0
	global_load_lds_dwordx4 v164, s[14:15]
	global_load_lds_dwordx4 v164, s[14:15] offset:1024
	s_add_u32 s14, s14, 0x2000
	s_addc_u32 s15, s15, 0
	v_mfma_f32_32x32x16_bf16 v[0:15], v[134:137], v[138:141], v[0:15]
	ds_read_b128 v[138:141], v162 offset:32768
	s_add_u32 m0, s20, 0x2000
	s_nop 0
	global_load_lds_dwordx4 v164, s[16:17]
	global_load_lds_dwordx4 v164, s[16:17] offset:1024
	s_add_u32 s16, s16, 0x2000
	s_addc_u32 s17, s17, 0
	v_mfma_f32_32x32x16_bf16 v[16:31], v[134:137], v[142:145], v[16:31]
	ds_read_b128 v[142:145], v162 offset:34816
	s_add_u32 m0, s20, 0x4000
	s_nop 0
	global_load_lds_dwordx4 v164, s[18:19]
	global_load_lds_dwordx4 v164, s[18:19] offset:1024
	s_add_u32 s18, s18, 0x2000
	s_addc_u32 s19, s19, 0
	v_mfma_f32_32x32x16_bf16 v[118:133], v[134:137], v[150:153], v[118:133]
	ds_read_b128 v[150:153], v162 offset:41984
	v_mfma_f32_32x32x16_bf16 v[66:81], v[134:137], v[154:157], v[66:81]
	ds_read_b128 v[154:157], v162 offset:44032
	ds_read_b128 v[134:137], v160 offset:26624
	s_waitcnt lgkmcnt(4)
	v_mfma_f32_32x32x16_bf16 v[32:47], v[82:85], v[138:141], v[32:47]
	s_waitcnt lgkmcnt(3)
	v_mfma_f32_32x32x16_bf16 v[48:63], v[82:85], v[142:145], v[48:63]
	s_waitcnt lgkmcnt(2)
	v_mfma_f32_32x32x16_bf16 v[86:101], v[82:85], v[150:153], v[86:101]
	s_waitcnt lgkmcnt(1)
	v_mfma_f32_32x32x16_bf16 v[102:117], v[82:85], v[154:157], v[102:117]
	ds_read_b128 v[82:85], v161 offset:24576
	s_waitcnt lgkmcnt(1)
	v_mfma_f32_32x32x16_bf16 v[66:81], v[134:137], v[154:157], v[66:81]
	ds_read_b128 v[154:157], v163 offset:44032
	v_mfma_f32_32x32x16_bf16 v[118:133], v[134:137], v[150:153], v[118:133]
	ds_read_b128 v[150:153], v163 offset:41984
	v_mfma_f32_32x32x16_bf16 v[16:31], v[134:137], v[142:145], v[16:31]
	ds_read_b128 v[142:145], v163 offset:34816
	v_mfma_f32_32x32x16_bf16 v[0:15], v[134:137], v[138:141], v[0:15]
	ds_read_b128 v[138:141], v163 offset:32768
	ds_read_b128 v[134:137], v161 offset:26624
	s_waitcnt lgkmcnt(4)
	v_mfma_f32_32x32x16_bf16 v[102:117], v[82:85], v[154:157], v[102:117]
	s_waitcnt lgkmcnt(3)
	v_mfma_f32_32x32x16_bf16 v[86:101], v[82:85], v[150:153], v[86:101]
	s_waitcnt lgkmcnt(2)
	v_mfma_f32_32x32x16_bf16 v[48:63], v[82:85], v[142:145], v[48:63]
	s_waitcnt lgkmcnt(1)
	v_mfma_f32_32x32x16_bf16 v[32:47], v[82:85], v[138:141], v[32:47]
	s_waitcnt vmcnt(0) lgkmcnt(0)
	s_barrier
	ds_read_b128 v[82:85], v160 offset:0
	s_add_u32 m0, s20, 0x6000
	s_nop 0
	global_load_lds_dwordx4 v164, s[14:15]
	global_load_lds_dwordx4 v164, s[14:15] offset:1024
	s_add_u32 s14, s14, 0x2000
	s_addc_u32 s15, s15, 0
	v_mfma_f32_32x32x16_bf16 v[0:15], v[134:137], v[138:141], v[0:15]
	ds_read_b128 v[138:141], v162 offset:8192
	s_add_u32 m0, s20, 0x8000
	s_nop 0
	global_load_lds_dwordx4 v164, s[16:17]
	global_load_lds_dwordx4 v164, s[16:17] offset:1024
	s_add_u32 s16, s16, 0x2000
	s_addc_u32 s17, s17, 0
	v_mfma_f32_32x32x16_bf16 v[16:31], v[134:137], v[142:145], v[16:31]
	ds_read_b128 v[142:145], v162 offset:10240
	s_add_u32 m0, s20, 0xa400
	s_nop 0
	global_load_lds_dwordx4 v164, s[18:19]
	global_load_lds_dwordx4 v164, s[18:19] offset:1024
	s_add_u32 s18, s18, 0x2000
	s_addc_u32 s19, s19, 0
	v_mfma_f32_32x32x16_bf16 v[118:133], v[134:137], v[150:153], v[118:133]
	ds_read_b128 v[150:153], v162 offset:16384
	v_mfma_f32_32x32x16_bf16 v[66:81], v[134:137], v[154:157], v[66:81]
	ds_read_b128 v[154:157], v162 offset:18432
	ds_read_b128 v[134:137], v160 offset:2048
	s_mov_b32 s21, 14
	.p2align 6

.Lg4a_cont:
	s_lshl3_add_u32 s30, s3, s33
	s_lshl_b32 s31, s4, 1
	s_mul_i32 s0, s30, 0xb0000
	s_add_u32 s22, s46, s0
	s_addc_u32 s23, s47, 0
	s_mul_i32 s0, s31, 0xb0000
	s_add_u32 s0, s0, 0x1880000
	s_add_u32 s24, s48, s0
	s_addc_u32 s25, s49, 0
	s_add_u32 s26, s24, 0xb0000
	s_addc_u32 s27, s25, 0
	s_waitcnt vmcnt(0) lgkmcnt(0)
	s_barrier
	s_add_u32 m0, s28, 0x0
	s_nop 0
	global_load_lds_dwordx4 v157, s[22:23]
	global_load_lds_dwordx4 v157, s[22:23] offset:1024
	s_add_u32 s22, s22, 0x2000
	s_addc_u32 s23, s23, 0
	s_add_u32 m0, s28, 0x2000
	s_nop 0
	global_load_lds_dwordx4 v157, s[24:25]
	global_load_lds_dwordx4 v157, s[24:25] offset:1024
	s_add_u32 s24, s24, 0x2000
	s_addc_u32 s25, s25, 0
	s_add_u32 m0, s28, 0x4000
	s_nop 0
	global_load_lds_dwordx4 v157, s[26:27]
	global_load_lds_dwordx4 v157, s[26:27] offset:1024
	s_add_u32 s26, s26, 0x2000
	s_addc_u32 s27, s27, 0
	s_waitcnt vmcnt(0)
	s_barrier
	s_add_u32 m0, s28, 0x6000
	s_nop 0
	global_load_lds_dwordx4 v157, s[22:23]
	global_load_lds_dwordx4 v157, s[22:23] offset:1024
	s_add_u32 s22, s22, 0x2000
	s_addc_u32 s23, s23, 0
	s_add_u32 m0, s28, 0x8000
	s_nop 0
	global_load_lds_dwordx4 v157, s[24:25]
	global_load_lds_dwordx4 v157, s[24:25] offset:1024
	s_add_u32 s24, s24, 0x2000
	s_addc_u32 s25, s25, 0
	s_add_u32 m0, s28, 0xa400
	s_nop 0
	global_load_lds_dwordx4 v157, s[26:27]
	global_load_lds_dwordx4 v157, s[26:27] offset:1024
	s_add_u32 s26, s26, 0x2000
	s_addc_u32 s27, s27, 0
	ds_read_b128 v[130:133], v81 offset:0
	ds_read_b128 v[138:141], v146 offset:8192
	ds_read_b128 v[150:153], v146 offset:10240
	ds_read_b128 v[160:163], v146 offset:16384
	ds_read_b128 v[164:167], v146 offset:18432
	ds_read_b128 v[134:137], v81 offset:2048
	s_waitcnt lgkmcnt(4)
	v_mfma_f32_32x32x16_bf16 v[64:79], v[130:133], v[138:141], 0
	s_waitcnt lgkmcnt(3)
	v_mfma_f32_32x32x16_bf16 v[48:63], v[130:133], v[150:153], 0
	s_waitcnt lgkmcnt(2)
	v_mfma_f32_32x32x16_bf16 v[82:97], v[130:133], v[160:163], 0
	s_waitcnt lgkmcnt(1)
	v_mfma_f32_32x32x16_bf16 v[98:113], v[130:133], v[164:167], 0
	ds_read_b128 v[130:133], v145 offset:0
	s_waitcnt lgkmcnt(1)
	v_mfma_f32_32x32x16_bf16 v[0:15], v[134:137], v[164:167], 0
	ds_read_b128 v[164:167], v147 offset:18432
	v_mfma_f32_32x32x16_bf16 v[114:129], v[134:137], v[160:163], 0
	ds_read_b128 v[160:163], v147 offset:16384
	v_mfma_f32_32x32x16_bf16 v[16:31], v[134:137], v[150:153], 0
	ds_read_b128 v[150:153], v147 offset:10240
	v_mfma_f32_32x32x16_bf16 v[32:47], v[134:137], v[138:141], 0
	ds_read_b128 v[138:141], v147 offset:8192
	ds_read_b128 v[134:137], v145 offset:2048
	s_waitcnt lgkmcnt(4)
	v_mfma_f32_32x32x16_bf16 v[98:113], v[130:133], v[164:167], v[98:113]
	s_waitcnt lgkmcnt(3)
	v_mfma_f32_32x32x16_bf16 v[82:97], v[130:133], v[160:163], v[82:97]
	s_waitcnt lgkmcnt(2)
	v_mfma_f32_32x32x16_bf16 v[48:63], v[130:133], v[150:153], v[48:63]
	s_waitcnt lgkmcnt(1)
	v_mfma_f32_32x32x16_bf16 v[64:79], v[130:133], v[138:141], v[64:79]
	s_waitcnt vmcnt(0) lgkmcnt(0)
	s_barrier
	ds_read_b128 v[130:133], v81 offset:24576
	s_add_u32 m0, s28, 0x0
	s_nop 0
	global_load_lds_dwordx4 v157, s[22:23]
	global_load_lds_dwordx4 v157, s[22:23] offset:1024
	s_add_u32 s22, s22, 0x2000
	s_addc_u32 s23, s23, 0
	v_mfma_f32_32x32x16_bf16 v[32:47], v[134:137], v[138:141], v[32:47]
	ds_read_b128 v[138:141], v146 offset:32768
	s_add_u32 m0, s28, 0x2000
	s_nop 0
	global_load_lds_dwordx4 v157, s[24:25]
	global_load_lds_dwordx4 v157, s[24:25] offset:1024
	s_add_u32 s24, s24, 0x2000
	s_addc_u32 s25, s25, 0
	v_mfma_f32_32x32x16_bf16 v[16:31], v[134:137], v[150:153], v[16:31]
	ds_read_b128 v[150:153], v146 offset:34816
	s_add_u32 m0, s28, 0x4000
	s_nop 0
	global_load_lds_dwordx4 v157, s[26:27]
	global_load_lds_dwordx4 v157, s[26:27] offset:1024
	s_add_u32 s26, s26, 0x2000
	s_addc_u32 s27, s27, 0
	v_mfma_f32_32x32x16_bf16 v[114:129], v[134:137], v[160:163], v[114:129]
	ds_read_b128 v[160:163], v146 offset:41984
	v_mfma_f32_32x32x16_bf16 v[0:15], v[134:137], v[164:167], v[0:15]
	ds_read_b128 v[164:167], v146 offset:44032
	ds_read_b128 v[134:137], v81 offset:26624
	s_waitcnt lgkmcnt(4)
	v_mfma_f32_32x32x16_bf16 v[64:79], v[130:133], v[138:141], v[64:79]
	s_waitcnt lgkmcnt(3)
	v_mfma_f32_32x32x16_bf16 v[48:63], v[130:133], v[150:153], v[48:63]
	s_waitcnt lgkmcnt(2)
	v_mfma_f32_32x32x16_bf16 v[82:97], v[130:133], v[160:163], v[82:97]
	s_waitcnt lgkmcnt(1)
	v_mfma_f32_32x32x16_bf16 v[98:113], v[130:133], v[164:167], v[98:113]
	ds_read_b128 v[130:133], v145 offset:24576
	s_waitcnt lgkmcnt(1)
	v_mfma_f32_32x32x16_bf16 v[0:15], v[134:137], v[164:167], v[0:15]
	ds_read_b128 v[164:167], v147 offset:44032
	v_mfma_f32_32x32x16_bf16 v[114:129], v[134:137], v[160:163], v[114:129]
	ds_read_b128 v[160:163], v147 offset:41984
	v_mfma_f32_32x32x16_bf16 v[16:31], v[134:137], v[150:153], v[16:31]
	ds_read_b128 v[150:153], v147 offset:34816
	v_mfma_f32_32x32x16_bf16 v[32:47], v[134:137], v[138:141], v[32:47]
	ds_read_b128 v[138:141], v147 offset:32768
	ds_read_b128 v[134:137], v145 offset:26624
	s_waitcnt lgkmcnt(4)
	v_mfma_f32_32x32x16_bf16 v[98:113], v[130:133], v[164:167], v[98:113]
	s_waitcnt lgkmcnt(3)
	v_mfma_f32_32x32x16_bf16 v[82:97], v[130:133], v[160:163], v[82:97]
	s_waitcnt lgkmcnt(2)
	v_mfma_f32_32x32x16_bf16 v[48:63], v[130:133], v[150:153], v[48:63]
	s_waitcnt lgkmcnt(1)
	v_mfma_f32_32x32x16_bf16 v[64:79], v[130:133], v[138:141], v[64:79]
	s_waitcnt vmcnt(0) lgkmcnt(0)
	s_barrier
	ds_read_b128 v[130:133], v81 offset:0
	s_add_u32 m0, s28, 0x6000
	s_nop 0
	global_load_lds_dwordx4 v157, s[22:23]
	global_load_lds_dwordx4 v157, s[22:23] offset:1024
	s_add_u32 s22, s22, 0x2000
	s_addc_u32 s23, s23, 0
	v_mfma_f32_32x32x16_bf16 v[32:47], v[134:137], v[138:141], v[32:47]
	ds_read_b128 v[138:141], v146 offset:8192
	s_add_u32 m0, s28, 0x8000
	s_nop 0
	global_load_lds_dwordx4 v157, s[24:25]
	global_load_lds_dwordx4 v157, s[24:25] offset:1024
	s_add_u32 s24, s24, 0x2000
	s_addc_u32 s25, s25, 0
	v_mfma_f32_32x32x16_bf16 v[16:31], v[134:137], v[150:153], v[16:31]
	ds_read_b128 v[150:153], v146 offset:10240
	s_add_u32 m0, s28, 0xa400
	s_nop 0
	global_load_lds_dwordx4 v157, s[26:27]
	global_load_lds_dwordx4 v157, s[26:27] offset:1024
	s_add_u32 s26, s26, 0x2000
	s_addc_u32 s27, s27, 0
	v_mfma_f32_32x32x16_bf16 v[114:129], v[134:137], v[160:163], v[114:129]
	ds_read_b128 v[160:163], v146 offset:16384
	v_mfma_f32_32x32x16_bf16 v[0:15], v[134:137], v[164:167], v[0:15]
	ds_read_b128 v[164:167], v146 offset:18432
	ds_read_b128 v[134:137], v81 offset:2048
	s_mov_b32 s29, 42
	.p2align 6

.LBB0_1048:
	v_add_u32_e32 v1, s4, v21
	v_mov_b64_e32 v[4:5], s[46:47]
	v_mad_i64_i32 v[32:33], s[0:1], v1, s50, v[4:5]
	s_lshl_b32 s14, s29, 1
	v_lshlrev_b32_e32 v2, 1, v38
	v_lshl_add_u64 v[4:5], v[32:33], 0, s[14:15]
	v_lshl_add_u64 v[4:5], v[4:5], 0, v[2:3]
	s_add_i32 s0, s29, s27
	v_add_co_u32_e32 v6, vcc, 0x1000, v4
	s_addk_i32 s0, 0x1300
	s_nop 0
	v_addc_co_u32_e32 v7, vcc, 0, v5, vcc
	v_or_b32_e32 v40, s0, v20
	v_add_co_u32_e32 v8, vcc, s39, v4
	v_lshlrev_b32_e32 v2, 1, v40
	s_nop 0
	v_addc_co_u32_e32 v9, vcc, 0, v5, vcc
	v_lshl_add_u64 v[32:33], v[32:33], 0, v[2:3]
	global_load_dwordx4 v[4:7], v[6:7], off offset:3584
	s_nop 0
	global_load_dwordx4 v[8:11], v[8:9], off offset:512
	v_lshlrev_b32_e32 v13, 4, v30
	global_load_ushort v39, v[32:33], off
	v_and_b32_e32 v2, 63, v30
	v_and_b32_e32 v13, 48, v13
	v_add_u32_e32 v13, v31, v13
	v_or_b32_e32 v2, 0x200, v2
	v_cmp_gt_u32_e32 vcc, 4, v20
	v_lshlrev_b32_e32 v43, 2, v31
	s_mov_b32 s30, 1
	v_cndmask_b32_e32 v2, v2, v13, vcc
	v_lshlrev_b32_e32 v13, 2, v38
	v_lshl_or_b32 v15, v21, 9, v13
	v_and_b32_e32 v13, 1, v30
	v_cmp_eq_u32_e64 s[0:1], 0, v13
	v_and_b32_e32 v13, 2, v30
	v_cmp_eq_u32_e64 s[4:5], 0, v13
	v_and_b32_e32 v13, -16, v30
	v_cndmask_b32_e64 v41, 0, 16, vcc
	v_lshlrev_b32_e32 v44, 2, v2
	v_or_b32_e32 v2, v13, v20
	s_mov_b32 s31, 0
	v_lshlrev_b32_e32 v17, 2, v30
	v_lshlrev_b32_e32 v21, 4, v20
	v_lshlrev_b32_e32 v45, 2, v2
	v_pk_add_f32 v[30:31], v[22:23], 1.0 op_sel_hi:[1,0] neg_lo:[1,0] neg_hi:[1,0]
	v_pk_add_f32 v[32:33], v[24:25], 1.0 op_sel_hi:[1,0] neg_lo:[1,0] neg_hi:[1,0]
	v_pk_add_f32 v[34:35], v[26:27], 1.0 op_sel_hi:[1,0] neg_lo:[1,0] neg_hi:[1,0]
	v_pk_add_f32 v[36:37], v[28:29], 1.0 op_sel_hi:[1,0] neg_lo:[1,0] neg_hi:[1,0]
	v_lshlrev_b32_e32 v46, 4, v41
	v_lshlrev_b32_e32 v47, 5, v41
	v_mul_u32_u24_e32 v48, 48, v41
	s_lshl_b32 s53, s28, 8
	v_lshlrev_b32_e32 v38, 1, v38
	v_lshlrev_b32_e32 v40, 1, v40
	v_lshlrev_b32_e32 v2, 1, v20
	v_add_u32_e32 v49, 0x6000, v43
	v_mov_b32_e32 v50, v1
	s_movk_i32 s77, 0x7400
	s_movk_i32 s78, 0x5400
	s_barrier
	s_branch .LBB0_1050
	.p2align 6

.LBB0_1092:
	v_add_u32_e32 v1, s10, v24
	v_mov_b64_e32 v[12:13], s[46:47]
	v_mad_i64_i32 v[26:27], s[2:3], v1, s50, v[12:13]
	v_mov_b64_e32 v[12:13], s[88:89]
	v_mad_i64_i32 v[14:15], s[2:3], v1, s52, v[12:13]
	s_lshl_b32 s2, s5, 6
	s_lshl_b32 s14, s5, 7
	v_lshl_add_u64 v[16:17], v[26:27], 0, s[14:15]
	v_lshlrev_b32_e32 v12, 1, v0
	v_mov_b32_e32 v13, v3
	s_or_b32 s3, s9, s2
	v_lshl_add_u64 v[16:17], v[16:17], 0, v[12:13]
	v_or_b32_e32 v2, s3, v10
	v_add_co_u32_e32 v18, vcc, s51, v16
	v_lshl_add_u64 v[14:15], v[14:15], 0, s[14:15]
	v_or_b32_e32 v28, 0xc00, v2
	v_addc_co_u32_e32 v19, vcc, 0, v17, vcc
	v_lshl_add_u64 v[22:23], v[14:15], 0, v[12:13]
	v_lshlrev_b32_e32 v2, 1, v28
	global_load_dwordx2 v[16:17], v[16:17], off offset:1024
	s_nop 0
	global_load_dwordx2 v[20:21], v[18:19], off offset:1024
	global_load_dwordx2 v[14:15], v[22:23], off
	s_nop 0
	global_load_dwordx2 v[18:19], v[22:23], off offset:1024
	s_nop 0
	global_load_dwordx2 v[22:23], v[22:23], off offset:2048
	v_lshl_add_u64 v[26:27], v[26:27], 0, v[2:3]
	global_load_ushort v27, v[26:27], off
	v_and_b32_e32 v2, 63, v11
	v_or_b32_e32 v2, 0x200, v2
	v_cmp_eq_u32_e32 vcc, 0, v10
	v_lshlrev_b32_e32 v30, 2, v0
	v_lshlrev_b32_e32 v32, 2, v11
	v_and_b32_e32 v11, -16, v11
	s_add_u32 s24, s88, s14
	v_cndmask_b32_e32 v2, v2, v25, vcc
	v_cndmask_b32_e64 v26, 0, 16, vcc
	v_lshl_or_b32 v31, v24, 8, v30
	v_or_b32_e32 v24, v11, v10
	s_addc_u32 s25, s89, 0
	s_mov_b32 s3, 1
	s_mov_b32 s10, 0
	v_lshlrev_b32_e32 v33, 2, v25
	v_mul_u32_u24_e32 v34, 60, v26
	v_lshlrev_b32_e32 v35, 2, v24
	v_lshlrev_b32_e32 v36, 2, v2
	v_lshlrev_b32_e32 v37, 3, v26
	v_mul_u32_u24_e32 v38, 12, v26
	v_lshlrev_b32_e32 v39, 4, v26
	v_mul_u32_u24_e32 v40, 20, v26
	v_mul_u32_u24_e32 v41, 24, v26
	v_mul_u32_u24_e32 v43, 28, v26
	v_lshlrev_b32_e32 v44, 5, v26
	v_mul_u32_u24_e32 v45, 36, v26
	v_mul_u32_u24_e32 v46, 40, v26
	v_mul_u32_u24_e32 v47, 44, v26
	v_mul_u32_u24_e32 v48, 48, v26
	v_mul_u32_u24_e32 v49, 52, v26
	v_mul_u32_u24_e32 v50, 56, v26
	v_lshl_add_u64 v[24:25], s[24:25], 0, v[12:13]
	v_mul_i32_i24_e32 v51, 0xffffffc8, v26
	s_lshl_b32 s11, s8, 8
	v_lshlrev_b32_e32 v26, 1, v28
	v_mov_b32_e32 v28, v1
	s_movk_i32 s76, 0x6400
	s_barrier
	s_branch .LBB0_1094
	.p2align 6

.Lg2b_cont:
	s_lshl3_add_u32 s30, s5, s33
	s_lshl_b32 s31, s6, 1
	s_mul_i32 s2, s30, 0x150000
	s_add_u32 s22, s46, s2
	s_addc_u32 s23, s47, 0
	s_mul_i32 s2, s31, 0x60000
	s_add_u32 s2, s2, 0xa80000
	s_add_u32 s24, s48, s2
	s_addc_u32 s25, s49, 0
	s_add_u32 s26, s24, 0x60000
	s_addc_u32 s27, s25, 0
	s_waitcnt vmcnt(0) lgkmcnt(0)
	s_barrier
	s_add_u32 m0, s28, 0x0
	s_nop 0
	global_load_lds_dwordx4 v166, s[22:23]
	s_add_u32 m0, s28, 0x400
	s_nop 0
	global_load_lds_dwordx4 v167, s[22:23]
	s_add_u32 s22, s22, 64
	s_addc_u32 s23, s23, 0
	s_add_u32 m0, s28, 0x2000
	s_nop 0
	global_load_lds_dwordx4 v165, s[24:25]
	global_load_lds_dwordx4 v165, s[24:25] offset:1024
	s_add_u32 s24, s24, 0x2000
	s_addc_u32 s25, s25, 0
	s_add_u32 m0, s28, 0x4000
	s_nop 0
	global_load_lds_dwordx4 v165, s[26:27]
	global_load_lds_dwordx4 v165, s[26:27] offset:1024
	s_add_u32 s26, s26, 0x2000
	s_addc_u32 s27, s27, 0
	s_waitcnt vmcnt(0)
	s_barrier
	s_add_u32 m0, s28, 0x6000
	s_nop 0
	global_load_lds_dwordx4 v166, s[22:23]
	s_add_u32 m0, s28, 0x6400
	s_nop 0
	global_load_lds_dwordx4 v167, s[22:23]
	s_add_u32 s22, s22, 64
	s_addc_u32 s23, s23, 0
	s_add_u32 m0, s28, 0x8000
	s_nop 0
	global_load_lds_dwordx4 v165, s[24:25]
	global_load_lds_dwordx4 v165, s[24:25] offset:1024
	s_add_u32 s24, s24, 0x2000
	s_addc_u32 s25, s25, 0
	s_add_u32 m0, s28, 0xa400
	s_nop 0
	global_load_lds_dwordx4 v165, s[26:27]
	global_load_lds_dwordx4 v165, s[26:27] offset:1024
	s_add_u32 s26, s26, 0x2000
	s_addc_u32 s27, s27, 0
	ds_read_b128 v[64:67], v151 offset:0
	ds_read_b128 v[72:75], v157 offset:8192
	ds_read_b128 v[126:129], v157 offset:10240
	ds_read_b128 v[152:155], v157 offset:16384
	ds_read_b128 v[160:163], v157 offset:18432
	ds_read_b128 v[68:71], v151 offset:2048
	s_waitcnt lgkmcnt(4)
	v_mfma_f32_32x32x16_bf16 v[48:63], v[64:67], v[72:75], 0
	s_waitcnt lgkmcnt(3)
	v_mfma_f32_32x32x16_bf16 v[32:47], v[64:67], v[126:129], 0
	s_waitcnt lgkmcnt(2)
	v_mfma_f32_32x32x16_bf16 v[78:93], v[64:67], v[152:155], 0
	s_waitcnt lgkmcnt(1)
	v_mfma_f32_32x32x16_bf16 v[94:109], v[64:67], v[160:163], 0
	ds_read_b128 v[64:67], v156 offset:0
	s_waitcnt lgkmcnt(1)
	v_mfma_f32_32x32x16_bf16 v[132:147], v[68:71], v[160:163], 0
	ds_read_b128 v[160:163], v164 offset:18432
	v_mfma_f32_32x32x16_bf16 v[110:125], v[68:71], v[152:155], 0
	ds_read_b128 v[152:155], v164 offset:16384
	v_mfma_f32_32x32x16_bf16 v[0:15], v[68:71], v[126:129], 0
	ds_read_b128 v[126:129], v164 offset:10240
	v_mfma_f32_32x32x16_bf16 v[16:31], v[68:71], v[72:75], 0
	ds_read_b128 v[72:75], v164 offset:8192
	ds_read_b128 v[68:71], v156 offset:2048
	s_waitcnt lgkmcnt(4)
	v_mfma_f32_32x32x16_bf16 v[94:109], v[64:67], v[160:163], v[94:109]
	s_waitcnt lgkmcnt(3)
	v_mfma_f32_32x32x16_bf16 v[78:93], v[64:67], v[152:155], v[78:93]
	s_waitcnt lgkmcnt(2)
	v_mfma_f32_32x32x16_bf16 v[32:47], v[64:67], v[126:129], v[32:47]
	s_waitcnt lgkmcnt(1)
	v_mfma_f32_32x32x16_bf16 v[48:63], v[64:67], v[72:75], v[48:63]
	s_waitcnt vmcnt(0) lgkmcnt(0)
	s_barrier
	ds_read_b128 v[64:67], v151 offset:24576
	s_add_u32 m0, s28, 0x0
	s_nop 0
	global_load_lds_dwordx4 v166, s[22:23]
	s_add_u32 m0, s28, 0x400
	s_nop 0
	global_load_lds_dwordx4 v167, s[22:23]
	s_add_u32 s22, s22, 64
	s_addc_u32 s23, s23, 0
	v_mfma_f32_32x32x16_bf16 v[16:31], v[68:71], v[72:75], v[16:31]
	ds_read_b128 v[72:75], v157 offset:32768
	s_add_u32 m0, s28, 0x2000
	s_nop 0
	global_load_lds_dwordx4 v165, s[24:25]
	global_load_lds_dwordx4 v165, s[24:25] offset:1024
	s_add_u32 s24, s24, 0x2000
	s_addc_u32 s25, s25, 0
	v_mfma_f32_32x32x16_bf16 v[0:15], v[68:71], v[126:129], v[0:15]
	ds_read_b128 v[126:129], v157 offset:34816
	s_add_u32 m0, s28, 0x4000
	s_nop 0
	global_load_lds_dwordx4 v165, s[26:27]
	global_load_lds_dwordx4 v165, s[26:27] offset:1024
	s_add_u32 s26, s26, 0x2000
	s_addc_u32 s27, s27, 0
	v_mfma_f32_32x32x16_bf16 v[110:125], v[68:71], v[152:155], v[110:125]
	ds_read_b128 v[152:155], v157 offset:41984
	v_mfma_f32_32x32x16_bf16 v[132:147], v[68:71], v[160:163], v[132:147]
	ds_read_b128 v[160:163], v157 offset:44032
	ds_read_b128 v[68:71], v151 offset:26624
	s_waitcnt lgkmcnt(4)
	v_mfma_f32_32x32x16_bf16 v[48:63], v[64:67], v[72:75], v[48:63]
	s_waitcnt lgkmcnt(3)
	v_mfma_f32_32x32x16_bf16 v[32:47], v[64:67], v[126:129], v[32:47]
	s_waitcnt lgkmcnt(2)
	v_mfma_f32_32x32x16_bf16 v[78:93], v[64:67], v[152:155], v[78:93]
	s_waitcnt lgkmcnt(1)
	v_mfma_f32_32x32x16_bf16 v[94:109], v[64:67], v[160:163], v[94:109]
	ds_read_b128 v[64:67], v156 offset:24576
	s_waitcnt lgkmcnt(1)
	v_mfma_f32_32x32x16_bf16 v[132:147], v[68:71], v[160:163], v[132:147]
	ds_read_b128 v[160:163], v164 offset:44032
	v_mfma_f32_32x32x16_bf16 v[110:125], v[68:71], v[152:155], v[110:125]
	ds_read_b128 v[152:155], v164 offset:41984
	v_mfma_f32_32x32x16_bf16 v[0:15], v[68:71], v[126:129], v[0:15]
	ds_read_b128 v[126:129], v164 offset:34816
	v_mfma_f32_32x32x16_bf16 v[16:31], v[68:71], v[72:75], v[16:31]
	ds_read_b128 v[72:75], v164 offset:32768
	ds_read_b128 v[68:71], v156 offset:26624
	s_waitcnt lgkmcnt(4)
	v_mfma_f32_32x32x16_bf16 v[94:109], v[64:67], v[160:163], v[94:109]
	s_waitcnt lgkmcnt(3)
	v_mfma_f32_32x32x16_bf16 v[78:93], v[64:67], v[152:155], v[78:93]
	s_waitcnt lgkmcnt(2)
	v_mfma_f32_32x32x16_bf16 v[32:47], v[64:67], v[126:129], v[32:47]
	s_waitcnt lgkmcnt(1)
	v_mfma_f32_32x32x16_bf16 v[48:63], v[64:67], v[72:75], v[48:63]
	s_waitcnt vmcnt(0) lgkmcnt(0)
	s_barrier
	ds_read_b128 v[64:67], v151 offset:0
	s_add_u32 m0, s28, 0x6000
	s_nop 0
	global_load_lds_dwordx4 v166, s[22:23]
	s_add_u32 m0, s28, 0x6400
	s_nop 0
	global_load_lds_dwordx4 v167, s[22:23]
	s_add_u32 s22, s22, 64
	s_addc_u32 s23, s23, 0
	v_mfma_f32_32x32x16_bf16 v[16:31], v[68:71], v[72:75], v[16:31]
	ds_read_b128 v[72:75], v157 offset:8192
	s_add_u32 m0, s28, 0x8000
	s_nop 0
	global_load_lds_dwordx4 v165, s[24:25]
	global_load_lds_dwordx4 v165, s[24:25] offset:1024
	s_add_u32 s24, s24, 0x2000
	s_addc_u32 s25, s25, 0
	v_mfma_f32_32x32x16_bf16 v[0:15], v[68:71], v[126:129], v[0:15]
	ds_read_b128 v[126:129], v157 offset:10240
	s_add_u32 m0, s28, 0xa400
	s_nop 0
	global_load_lds_dwordx4 v165, s[26:27]
	global_load_lds_dwordx4 v165, s[26:27] offset:1024
	s_add_u32 s26, s26, 0x2000
	s_addc_u32 s27, s27, 0
	v_mfma_f32_32x32x16_bf16 v[110:125], v[68:71], v[152:155], v[110:125]
	ds_read_b128 v[152:155], v157 offset:16384
	v_mfma_f32_32x32x16_bf16 v[132:147], v[68:71], v[160:163], v[132:147]
	ds_read_b128 v[160:163], v157 offset:18432
	ds_read_b128 v[68:71], v151 offset:2048
	s_mov_b32 s29, 22
	.p2align 6

.Lg3b_cont:
	s_lshl3_add_u32 s26, s6, s29
	s_lshl_b32 s27, s7, 1
	s_mul_i32 s1, s26, 0x40000
	s_add_u32 s18, s44, s1
	s_addc_u32 s19, s45, 0
	s_mul_i32 s1, s27, 0x40000
	s_add_u32 s1, s1, 0xd80000
	s_add_u32 s20, s48, s1
	s_addc_u32 s21, s49, 0
	s_add_u32 s22, s20, 0x40000
	s_addc_u32 s23, s21, 0
	s_lshl_b32 s1, s26, 9
	s_add_u32 s34, s2, s1
	s_addc_u32 s35, s3, 0
	s_waitcnt vmcnt(0) lgkmcnt(0)
	s_barrier
	v_and_b32_e32 v167, 63, v148
	v_lshlrev_b32_e32 v167, 4, v167
	s_mov_b32 m0, 0xc400
	s_mov_b64 exec, 0xffffffff
	global_load_lds_dwordx4 v167, s[34:35]
	s_mov_b64 exec, -1
	s_add_u32 m0, s24, 0x0
	s_nop 0
	global_load_lds_dwordx4 v164, s[18:19]
	global_load_lds_dwordx4 v164, s[18:19] offset:1024
	s_add_u32 s18, s18, 0x2000
	s_addc_u32 s19, s19, 0
	s_add_u32 m0, s24, 0x2000
	s_nop 0
	global_load_lds_dwordx4 v164, s[20:21]
	global_load_lds_dwordx4 v164, s[20:21] offset:1024
	s_add_u32 s20, s20, 0x2000
	s_addc_u32 s21, s21, 0
	s_add_u32 m0, s24, 0x4000
	s_nop 0
	global_load_lds_dwordx4 v164, s[22:23]
	global_load_lds_dwordx4 v164, s[22:23] offset:1024
	s_add_u32 s22, s22, 0x2000
	s_addc_u32 s23, s23, 0
	s_waitcnt vmcnt(0)
	s_barrier
	s_add_u32 m0, s24, 0x6000
	s_nop 0
	global_load_lds_dwordx4 v164, s[18:19]
	global_load_lds_dwordx4 v164, s[18:19] offset:1024
	s_add_u32 s18, s18, 0x2000
	s_addc_u32 s19, s19, 0
	s_add_u32 m0, s24, 0x8000
	s_nop 0
	global_load_lds_dwordx4 v164, s[20:21]
	global_load_lds_dwordx4 v164, s[20:21] offset:1024
	s_add_u32 s20, s20, 0x2000
	s_addc_u32 s21, s21, 0
	s_add_u32 m0, s24, 0xa400
	s_nop 0
	global_load_lds_dwordx4 v164, s[22:23]
	global_load_lds_dwordx4 v164, s[22:23] offset:1024
	s_add_u32 s22, s22, 0x2000
	s_addc_u32 s23, s23, 0
	ds_read_b128 v[64:67], v160 offset:0
	ds_read_b128 v[90:93], v162 offset:8192
	ds_read_b128 v[142:145], v162 offset:10240
	ds_read_b128 v[150:153], v162 offset:16384
	ds_read_b128 v[154:157], v162 offset:18432
	ds_read_b128 v[68:71], v160 offset:2048
	s_waitcnt lgkmcnt(4)
	v_mfma_f32_32x32x16_bf16 v[48:63], v[64:67], v[90:93], 0
	s_waitcnt lgkmcnt(3)
	v_mfma_f32_32x32x16_bf16 v[32:47], v[64:67], v[142:145], 0
	s_waitcnt lgkmcnt(2)
	v_mfma_f32_32x32x16_bf16 v[94:109], v[64:67], v[150:153], 0
	s_waitcnt lgkmcnt(1)
	v_mfma_f32_32x32x16_bf16 v[110:125], v[64:67], v[154:157], 0
	ds_read_b128 v[64:67], v161 offset:0
	s_waitcnt lgkmcnt(1)
	v_mfma_f32_32x32x16_bf16 v[74:89], v[68:71], v[154:157], 0
	ds_read_b128 v[154:157], v163 offset:18432
	v_mfma_f32_32x32x16_bf16 v[126:141], v[68:71], v[150:153], 0
	ds_read_b128 v[150:153], v163 offset:16384
	v_mfma_f32_32x32x16_bf16 v[0:15], v[68:71], v[142:145], 0
	ds_read_b128 v[142:145], v163 offset:10240
	v_mfma_f32_32x32x16_bf16 v[16:31], v[68:71], v[90:93], 0
	ds_read_b128 v[90:93], v163 offset:8192
	ds_read_b128 v[68:71], v161 offset:2048
	s_waitcnt lgkmcnt(4)
	v_mfma_f32_32x32x16_bf16 v[110:125], v[64:67], v[154:157], v[110:125]
	s_waitcnt lgkmcnt(3)
	v_mfma_f32_32x32x16_bf16 v[94:109], v[64:67], v[150:153], v[94:109]
	s_waitcnt lgkmcnt(2)
	v_mfma_f32_32x32x16_bf16 v[32:47], v[64:67], v[142:145], v[32:47]
	s_waitcnt lgkmcnt(1)
	v_mfma_f32_32x32x16_bf16 v[48:63], v[64:67], v[90:93], v[48:63]
	s_waitcnt vmcnt(0) lgkmcnt(0)
	s_barrier
	ds_read_b128 v[64:67], v160 offset:24576
	s_add_u32 m0, s24, 0x0
	s_nop 0
	global_load_lds_dwordx4 v164, s[18:19]
	global_load_lds_dwordx4 v164, s[18:19] offset:1024
	s_add_u32 s18, s18, 0x2000
	s_addc_u32 s19, s19, 0
	v_mfma_f32_32x32x16_bf16 v[16:31], v[68:71], v[90:93], v[16:31]
	ds_read_b128 v[90:93], v162 offset:32768
	s_add_u32 m0, s24, 0x2000
	s_nop 0
	global_load_lds_dwordx4 v164, s[20:21]
	global_load_lds_dwordx4 v164, s[20:21] offset:1024
	s_add_u32 s20, s20, 0x2000
	s_addc_u32 s21, s21, 0
	v_mfma_f32_32x32x16_bf16 v[0:15], v[68:71], v[142:145], v[0:15]
	ds_read_b128 v[142:145], v162 offset:34816
	s_add_u32 m0, s24, 0x4000
	s_nop 0
	global_load_lds_dwordx4 v164, s[22:23]
	global_load_lds_dwordx4 v164, s[22:23] offset:1024
	s_add_u32 s22, s22, 0x2000
	s_addc_u32 s23, s23, 0
	v_mfma_f32_32x32x16_bf16 v[126:141], v[68:71], v[150:153], v[126:141]
	ds_read_b128 v[150:153], v162 offset:41984
	v_mfma_f32_32x32x16_bf16 v[74:89], v[68:71], v[154:157], v[74:89]
	ds_read_b128 v[154:157], v162 offset:44032
	ds_read_b128 v[68:71], v160 offset:26624
	s_waitcnt lgkmcnt(4)
	v_mfma_f32_32x32x16_bf16 v[48:63], v[64:67], v[90:93], v[48:63]
	s_waitcnt lgkmcnt(3)
	v_mfma_f32_32x32x16_bf16 v[32:47], v[64:67], v[142:145], v[32:47]
	s_waitcnt lgkmcnt(2)
	v_mfma_f32_32x32x16_bf16 v[94:109], v[64:67], v[150:153], v[94:109]
	s_waitcnt lgkmcnt(1)
	v_mfma_f32_32x32x16_bf16 v[110:125], v[64:67], v[154:157], v[110:125]
	ds_read_b128 v[64:67], v161 offset:24576
	s_waitcnt lgkmcnt(1)
	v_mfma_f32_32x32x16_bf16 v[74:89], v[68:71], v[154:157], v[74:89]
	ds_read_b128 v[154:157], v163 offset:44032
	v_mfma_f32_32x32x16_bf16 v[126:141], v[68:71], v[150:153], v[126:141]
	ds_read_b128 v[150:153], v163 offset:41984
	v_mfma_f32_32x32x16_bf16 v[0:15], v[68:71], v[142:145], v[0:15]
	ds_read_b128 v[142:145], v163 offset:34816
	v_mfma_f32_32x32x16_bf16 v[16:31], v[68:71], v[90:93], v[16:31]
	ds_read_b128 v[90:93], v163 offset:32768
	ds_read_b128 v[68:71], v161 offset:26624
	s_waitcnt lgkmcnt(4)
	v_mfma_f32_32x32x16_bf16 v[110:125], v[64:67], v[154:157], v[110:125]
	s_waitcnt lgkmcnt(3)
	v_mfma_f32_32x32x16_bf16 v[94:109], v[64:67], v[150:153], v[94:109]
	s_waitcnt lgkmcnt(2)
	v_mfma_f32_32x32x16_bf16 v[32:47], v[64:67], v[142:145], v[32:47]
	s_waitcnt lgkmcnt(1)
	v_mfma_f32_32x32x16_bf16 v[48:63], v[64:67], v[90:93], v[48:63]
	s_waitcnt vmcnt(0) lgkmcnt(0)
	s_barrier
	ds_read_b128 v[64:67], v160 offset:0
	s_add_u32 m0, s24, 0x6000
	s_nop 0
	global_load_lds_dwordx4 v164, s[18:19]
	global_load_lds_dwordx4 v164, s[18:19] offset:1024
	s_add_u32 s18, s18, 0x2000
	s_addc_u32 s19, s19, 0
	v_mfma_f32_32x32x16_bf16 v[16:31], v[68:71], v[90:93], v[16:31]
	ds_read_b128 v[90:93], v162 offset:8192
	s_add_u32 m0, s24, 0x8000
	s_nop 0
	global_load_lds_dwordx4 v164, s[20:21]
	global_load_lds_dwordx4 v164, s[20:21] offset:1024
	s_add_u32 s20, s20, 0x2000
	s_addc_u32 s21, s21, 0
	v_mfma_f32_32x32x16_bf16 v[0:15], v[68:71], v[142:145], v[0:15]
	ds_read_b128 v[142:145], v162 offset:10240
	s_add_u32 m0, s24, 0xa400
	s_nop 0
	global_load_lds_dwordx4 v164, s[22:23]
	global_load_lds_dwordx4 v164, s[22:23] offset:1024
	s_add_u32 s22, s22, 0x2000
	s_addc_u32 s23, s23, 0
	v_mfma_f32_32x32x16_bf16 v[126:141], v[68:71], v[150:153], v[126:141]
	ds_read_b128 v[150:153], v162 offset:16384
	v_mfma_f32_32x32x16_bf16 v[74:89], v[68:71], v[154:157], v[74:89]
	ds_read_b128 v[154:157], v162 offset:18432
	ds_read_b128 v[68:71], v160 offset:2048
	s_mov_b32 s25, 14
	.p2align 6
